# rot epilogue preload + conv taps staged in LDS (raw-row prefetch no longer drained per item)
# speedup vs baseline: 1.0051x; 1.0051x over previous
.LBB0_929:
	s_cmp_lt_i32 s86, 6
	s_cselect_b64 s[2:3], -1, 0
	s_and_b64 s[2:3], s[2:3], s[0:1]
	s_andn2_b64 vcc, exec, s[2:3]
	s_cbranch_vccnz .LBB0_967
	s_add_i32 s0, 0, 0x27e68
	v_mov_b32_e32 v0, s0
	ds_read2_b64 v[0:3], v0 offset1:1
	s_cmpk_gt_i32 s81, 0x2fff
	s_waitcnt lgkmcnt(0)
	v_readfirstlane_b32 s4, v0
	v_readfirstlane_b32 s5, v1
	v_readfirstlane_b32 s6, v2
	v_readfirstlane_b32 s7, v3
	s_cbranch_scc1 .LBB0_967
	v_lshlrev_b32_e32 v123, 4, v182
	v_add_u32_e32 v132, 0x2000, v123
	v_add_u32_e32 v133, 0x4000, v123
	v_add_u32_e32 v134, 0x6000, v123
	global_load_dwordx4 v[124:127], v123, s[4:5]
	global_load_dwordx4 v[128:131], v132, s[4:5]
	global_load_dwordx4 v[136:139], v133, s[4:5]
	v_cmp_gt_u32_e32 vcc, 0x180, v182
	s_and_saveexec_b64 s[40:41], vcc
	global_load_dwordx4 v[140:143], v134, s[4:5]
	global_load_dwordx4 v[144:147], v123, s[6:7]
	s_or_b64 exec, exec, s[40:41]
	v_add_u32_e32 v135, 0x8000, v123
	s_waitcnt vmcnt(0)
	ds_write_b128 v135, v[124:127]
	ds_write_b128 v135, v[128:131] offset:8192
	ds_write_b128 v135, v[136:139] offset:16384
	s_and_saveexec_b64 s[40:41], vcc
	ds_write_b128 v135, v[140:143] offset:24576
	ds_write_b128 v135, v[144:147] offset:30720
	s_or_b64 exec, exec, s[40:41]
	s_waitcnt lgkmcnt(0)
	s_barrier
	s_add_u32 s8, s84, 0x14000000
	s_addc_u32 s9, s85, 0
	s_ashr_i32 s0, s81, 31
	s_lshr_b32 s0, s0, 23
	s_add_i32 s0, s81, s0
	s_ashr_i32 s1, s0, 9
	s_and_b32 s0, s0, 0x1fffe00
	v_lshrrev_b32_e32 v0, 2, v182
	s_sub_i32 s0, s81, s0
	v_and_b32_e32 v68, 0xfe, v0
	s_lshl_b32 s0, s0, 7
	s_and_b32 s15, s0, 0x780
	v_add_u32_e32 v69, -2, v68
	v_add_u32_e32 v5, s15, v69
	s_and_b32 s14, s0, 0xfffff800
	v_add_u32_e32 v0, s14, v5
	s_movk_i32 s0, 0x1600
	v_mov_b32_e32 v38, 0
	v_mul_lo_u32 v0, v0, s0
	v_and_b32_e32 v4, 7, v182
	s_lshl_b32 s12, s1, 6
	v_ashrrev_i32_e32 v1, 31, v0
	v_mov_b32_e32 v40, v38
	v_mov_b32_e32 v41, v38
	s_ashr_i32 s13, s12, 31
	v_lshlrev_b32_e32 v70, 3, v4
	v_lshl_add_u64 v[0:1], v[0:1], 1, s[8:9]
	s_movk_i32 s0, 0x800
	v_mov_b32_e32 v39, v38
	v_mov_b64_e32 v[48:49], v[40:41]
	v_cmp_gt_u32_e64 s[0:1], s0, v5
	v_lshl_add_u64 v[0:1], s[12:13], 1, v[0:1]
	v_lshlrev_b32_e32 v62, 1, v70
	v_mov_b64_e32 v[46:47], v[38:39]
	s_and_saveexec_b64 s[10:11], s[0:1]
	s_cbranch_execz .LBB0_933
	v_mov_b32_e32 v63, v38
	v_lshl_add_u64 v[2:3], v[0:1], 0, v[62:63]
	v_add_co_u32_e32 v2, vcc, 0x2000, v2
	s_nop 1
	v_addc_co_u32_e32 v3, vcc, 0, v3, vcc
	global_load_dwordx4 v[46:49], v[2:3], off

.LBB0_945:
	s_waitcnt vmcnt(2)
	v_mov_b64_e32 v[48:49], v[12:13]
	v_mov_b64_e32 v[40:41], v[8:9]
	v_mov_b64_e32 v[52:53], v[16:17]
	v_mov_b64_e32 v[28:29], v[20:21]
	v_mov_b64_e32 v[44:45], v[24:25]
	s_add_i32 s20, s20, s21
	s_andn2_b64 vcc, exec, s[12:13]
	v_mov_b64_e32 v[46:47], v[10:11]
	v_mov_b64_e32 v[38:39], v[6:7]
	v_mov_b64_e32 v[50:51], v[14:15]
	v_mov_b64_e32 v[26:27], v[18:19]
	v_mov_b64_e32 v[42:43], v[22:23]
	s_mov_b32 s31, s30
	v_mov_b32_e32 v30, v34
	v_mov_b32_e32 v31, v35
	v_mov_b32_e32 v32, v36
	v_mov_b32_e32 v33, v37
	s_cbranch_vccz .LBB0_967

.LBB0_960:
	s_ashr_i32 s0, s31, 31
	s_lshr_b32 s0, s0, 23
	s_add_i32 s1, s31, s0
	s_ashr_i32 s16, s1, 9
	s_lshl_b32 s0, s16, 6
	v_or_b32_e32 v4, s0, v70
	v_ashrrev_i32_e32 v5, 31, v4
	v_lshlrev_b64 v[4:5], 2, v[4:5]
	v_add_u32_e32 v123, 0x8000, v4
	v_lshl_add_u64 v[106:107], s[4:5], 0, v[4:5]
	v_lshl_add_u64 v[4:5], s[6:7], 0, v[4:5]
	ds_read_b128 v[58:61], v123 offset:30720
	ds_read_b128 v[74:77], v123
	ds_read_b128 v[78:81], v123 offset:16
	ds_read_b128 v[54:57], v123 offset:30736
	v_add_co_u32_e32 v4, vcc, s25, v106
	v_lshlrev_b32_e32 v112, 16, v38
	s_nop 0
	v_addc_co_u32_e32 v5, vcc, 0, v107, vcc
	v_add_co_u32_e32 v98, vcc, s26, v106
	ds_read_b128 v[82:85], v123 offset:6144
	ds_read_b128 v[86:89], v123 offset:6160
	v_addc_co_u32_e32 v99, vcc, 0, v107, vcc
	v_add_co_u32_e32 v4, vcc, s24, v106
	ds_read_b128 v[90:93], v123 offset:12288
	ds_read_b128 v[94:97], v123 offset:12304
	v_addc_co_u32_e32 v5, vcc, 0, v107, vcc
	ds_read_b128 v[98:101], v123 offset:18432
	ds_read_b128 v[102:105], v123 offset:18448
	v_add_co_u32_e32 v4, vcc, s27, v106
	v_and_b32_e32 v113, 0xffff0000, v38
	s_nop 0
	v_addc_co_u32_e32 v5, vcc, 0, v107, vcc
	v_lshlrev_b32_e32 v114, 16, v39
	v_and_b32_e32 v115, 0xffff0000, v39
	v_lshlrev_b32_e32 v116, 16, v40
	v_and_b32_e32 v117, 0xffff0000, v40
	v_lshlrev_b32_e32 v118, 16, v41
	v_and_b32_e32 v119, 0xffff0000, v41
	ds_read_b128 v[38:41], v123 offset:24576
	v_lshlrev_b32_e32 v3, 16, v46
	v_and_b32_e32 v63, 0xffff0000, v46
	v_lshlrev_b32_e32 v65, 16, v47
	v_and_b32_e32 v67, 0xffff0000, v47
	v_lshlrev_b32_e32 v108, 16, v48
	v_and_b32_e32 v109, 0xffff0000, v48
	v_lshlrev_b32_e32 v110, 16, v49
	v_and_b32_e32 v111, 0xffff0000, v49
	ds_read_b128 v[46:49], v123 offset:24592
	v_lshlrev_b32_e32 v120, 16, v50
	v_and_b32_e32 v50, 0xffff0000, v50
	v_lshlrev_b32_e32 v121, 16, v51
	v_and_b32_e32 v51, 0xffff0000, v51
	v_lshlrev_b32_e32 v122, 16, v52
	v_and_b32_e32 v52, 0xffff0000, v52
	v_lshlrev_b32_e32 v106, 16, v53
	v_and_b32_e32 v53, 0xffff0000, v53
	s_and_b32 s1, s1, 0xfffffe00
	s_sub_i32 s17, s31, s1
	s_ashr_i32 s33, s17, 4
	s_and_b32 s34, s20, 0x780
	s_cmpk_lt_i32 s31, 0x2000
	s_waitcnt lgkmcnt(0)
	v_fma_f32 v3, v74, v3, v58
	v_fma_f32 v4, v75, v63, v59
	v_fma_f32 v5, v76, v65, v60
	v_fma_f32 v63, v77, v67, v61
	v_fma_f32 v65, v78, v108, v54
	v_fma_f32 v67, v79, v109, v55
	v_fma_f32 v108, v81, v111, v57
	v_fma_f32 v58, v74, v112, v58
	v_fma_f32 v59, v75, v113, v59
	v_fmac_f32_e32 v61, v77, v115
	v_fma_f32 v55, v79, v117, v55
	v_fmac_f32_e32 v57, v81, v119
	v_fmac_f32_e32 v3, v82, v112
	v_fmac_f32_e32 v4, v83, v113
	v_fmac_f32_e32 v63, v85, v115
	v_fmac_f32_e32 v67, v87, v117
	v_fmac_f32_e32 v108, v89, v119
	v_fmac_f32_e32 v3, v90, v120
	v_fmac_f32_e32 v4, v91, v50
	v_fmac_f32_e32 v63, v93, v51
	v_fmac_f32_e32 v67, v95, v52
	v_fmac_f32_e32 v108, v97, v53
	v_fmac_f32_e32 v58, v82, v120
	v_fmac_f32_e32 v59, v83, v50
	v_fmac_f32_e32 v61, v85, v51
	v_fmac_f32_e32 v55, v87, v52
	v_fmac_f32_e32 v57, v89, v53
	v_lshlrev_b32_e32 v50, 16, v26
	v_and_b32_e32 v26, 0xffff0000, v26
	v_lshlrev_b32_e32 v51, 16, v27
	v_and_b32_e32 v27, 0xffff0000, v27
	v_lshlrev_b32_e32 v52, 16, v28
	v_and_b32_e32 v28, 0xffff0000, v28
	v_lshlrev_b32_e32 v53, 16, v29
	v_and_b32_e32 v29, 0xffff0000, v29
	v_fmac_f32_e32 v3, v98, v50
	v_fmac_f32_e32 v4, v99, v26
	v_fmac_f32_e32 v63, v101, v27
	v_fmac_f32_e32 v67, v103, v28
	v_fmac_f32_e32 v108, v105, v29
	v_fmac_f32_e32 v58, v90, v50
	v_fmac_f32_e32 v59, v91, v26
	v_fmac_f32_e32 v61, v93, v27
	v_fmac_f32_e32 v55, v95, v28
	v_fmac_f32_e32 v57, v97, v29
	v_lshlrev_b32_e32 v26, 16, v42
	v_and_b32_e32 v27, 0xffff0000, v42
	v_lshlrev_b32_e32 v28, 16, v43
	v_and_b32_e32 v29, 0xffff0000, v43
	v_lshlrev_b32_e32 v42, 16, v44
	v_and_b32_e32 v43, 0xffff0000, v44
	v_lshlrev_b32_e32 v44, 16, v45
	v_and_b32_e32 v45, 0xffff0000, v45
	v_fma_f32 v60, v76, v114, v60
	v_fmac_f32_e32 v3, v38, v26
	v_fmac_f32_e32 v58, v98, v26
	v_fmac_f32_e32 v57, v105, v45
	v_and_b32_e32 v26, 0xffff0000, v33
	v_fmac_f32_e32 v60, v84, v121
	v_fmac_f32_e32 v57, v49, v26
	v_lshlrev_b32_e32 v26, 16, v30
	v_fma_f32 v54, v78, v116, v54
	v_fmac_f32_e32 v60, v92, v51
	v_fmac_f32_e32 v59, v99, v27
	v_fmac_f32_e32 v58, v38, v26
	v_and_b32_e32 v26, 0xffff0000, v30
	v_fma_f32 v107, v80, v110, v56
	v_fma_f32 v56, v80, v118, v56
	v_fmac_f32_e32 v5, v84, v114
	v_fmac_f32_e32 v54, v86, v122
	v_fmac_f32_e32 v60, v100, v28
	v_fmac_f32_e32 v59, v39, v26
	v_lshlrev_b32_e32 v26, 16, v31
	v_fmac_f32_e32 v5, v92, v121
	v_fmac_f32_e32 v56, v88, v106
	v_fmac_f32_e32 v54, v94, v52
	v_fmac_f32_e32 v61, v101, v29
	v_fmac_f32_e32 v60, v40, v26
	v_and_b32_e32 v26, 0xffff0000, v31
	v_fmac_f32_e32 v5, v100, v51
	v_fmac_f32_e32 v56, v96, v53
	v_fmac_f32_e32 v54, v102, v42
	v_fmac_f32_e32 v61, v41, v26
	v_lshlrev_b32_e32 v26, 16, v32
	v_fmac_f32_e32 v5, v40, v28
	v_fmac_f32_e32 v55, v103, v43
	v_fmac_f32_e32 v56, v104, v44
	v_fmac_f32_e32 v54, v46, v26
	v_and_b32_e32 v26, 0xffff0000, v32
	v_lshlrev_b32_e32 v28, 16, v33
	v_fmac_f32_e32 v55, v47, v26
	v_mul_f32_e32 v26, 0xbfb8aa3b, v3
	v_fmac_f32_e32 v56, v48, v28
	v_mul_f32_e32 v28, 0xbfb8aa3b, v5
	v_exp_f32_e32 v26, v26
	v_exp_f32_e32 v28, v28
	v_fmac_f32_e32 v4, v39, v27
	v_fmac_f32_e32 v63, v41, v29
	v_add_f32_e32 v26, 1.0, v26
	v_mul_f32_e32 v29, 0xbfb8aa3b, v4
	v_add_f32_e32 v28, 1.0, v28
	v_rcp_f32_e32 v26, v26
	v_exp_f32_e32 v29, v29
	v_rcp_f32_e32 v28, v28
	v_fmac_f32_e32 v65, v86, v116
	v_mul_f32_e32 v3, v3, v26
	v_add_f32_e32 v26, 1.0, v29
	v_mul_f32_e32 v29, 0xbfb8aa3b, v60
	v_mul_f32_e32 v5, v5, v28
	v_mul_f32_e32 v28, 0xbfb8aa3b, v61
	v_rcp_f32_e32 v26, v26
	v_exp_f32_e32 v29, v29
	v_exp_f32_e32 v28, v28
	v_fmac_f32_e32 v65, v94, v122
	v_fmac_f32_e32 v65, v102, v52
	v_fmac_f32_e32 v65, v46, v42
	v_mul_f32_e32 v27, 0xbfb8aa3b, v58
	v_mul_f32_e32 v4, v4, v26
	v_add_f32_e32 v26, 1.0, v29
	v_add_f32_e32 v28, 1.0, v28
	v_mul_f32_e32 v29, 0xbfb8aa3b, v65
	v_exp_f32_e32 v27, v27
	v_rcp_f32_e32 v26, v26
	v_rcp_f32_e32 v28, v28
	v_exp_f32_e32 v29, v29
	v_fmac_f32_e32 v67, v47, v43
	v_add_f32_e32 v27, 1.0, v27
	v_mul_f32_e32 v32, v60, v26
	v_mul_f32_e32 v33, v61, v28
	v_add_f32_e32 v26, 1.0, v29
	v_mul_f32_e32 v28, 0xbfb8aa3b, v54
	v_mul_f32_e32 v29, 0xbfb8aa3b, v67
	v_rcp_f32_e32 v27, v27
	v_exp_f32_e32 v28, v28
	v_exp_f32_e32 v29, v29
	v_mul_f32_e32 v38, 0xbfb8aa3b, v55
	v_mul_f32_e32 v30, v58, v27
	v_mul_f32_e32 v27, 0xbfb8aa3b, v59
	v_add_f32_e32 v28, 1.0, v28
	v_add_f32_e32 v29, 1.0, v29
	v_fmac_f32_e32 v107, v88, v118
	v_exp_f32_e32 v27, v27
	v_rcp_f32_e32 v26, v26
	v_rcp_f32_e32 v28, v28
	v_rcp_f32_e32 v29, v29
	v_exp_f32_e32 v38, v38
	v_fmac_f32_e32 v107, v96, v106
	v_fmac_f32_e32 v107, v104, v53
	v_fmac_f32_e32 v107, v48, v44
	v_add_f32_e32 v27, 1.0, v27
	v_mul_f32_e32 v39, v65, v26
	v_mul_f32_e32 v40, v54, v28
	v_mul_f32_e32 v28, v67, v29
	v_add_f32_e32 v26, 1.0, v38
	v_mul_f32_e32 v29, 0xbfb8aa3b, v107
	v_mul_f32_e32 v38, 0xbfb8aa3b, v56
	v_rcp_f32_e32 v27, v27
	v_rcp_f32_e32 v26, v26
	v_exp_f32_e32 v29, v29
	v_exp_f32_e32 v38, v38
	v_fmac_f32_e32 v108, v49, v45
	v_mul_f32_e32 v31, v59, v27
	v_mul_f32_e32 v27, 0xbfb8aa3b, v63
	v_mul_f32_e32 v41, v55, v26
	v_add_f32_e32 v26, 1.0, v29
	v_add_f32_e32 v29, 1.0, v38
	v_mul_f32_e32 v38, 0xbfb8aa3b, v108
	v_exp_f32_e32 v27, v27
	v_exp_f32_e32 v38, v38
	v_mul_f32_e32 v42, 0xbfb8aa3b, v57
	v_exp_f32_e32 v42, v42
	v_add_f32_e32 v27, 1.0, v27
	v_add_f32_e32 v38, 1.0, v38
	v_rcp_f32_e32 v27, v27
	v_rcp_f32_e32 v29, v29
	v_rcp_f32_e32 v38, v38
	v_add_f32_e32 v42, 1.0, v42
	v_rcp_f32_e32 v26, v26
	v_rcp_f32_e32 v42, v42
	v_mul_f32_e32 v27, v63, v27
	v_mul_f32_e32 v44, v56, v29
	v_mul_f32_e32 v29, v108, v38
	v_mul_f32_e32 v43, v107, v26
	v_mul_f32_e32 v38, v57, v42
	v_cvt_pk_bf16_f32 v26, v3, v4
	v_cvt_pk_bf16_f32 v27, v5, v27
	v_cvt_pk_bf16_f32 v28, v39, v28
	v_cvt_pk_bf16_f32 v29, v43, v29
	v_cvt_pk_bf16_f32 v30, v30, v31
	v_cvt_pk_bf16_f32 v31, v32, v33
	v_cvt_pk_bf16_f32 v32, v40, v41
	v_cvt_pk_bf16_f32 v33, v44, v38
	s_cbranch_scc1 .LBB0_962
	s_cmpk_lt_u32 s31, 0x2800
	v_and_or_b32 v3, s0, 64, v70
	s_cselect_b32 s0, s29, 0xc000000
	s_add_u32 s0, s10, s0
	s_addc_u32 s1, s11, 0
	s_lshl_b32 s15, s16, 10
	s_lshl_b32 s14, s33, 12
	s_and_b32 s15, s15, 0x800
	s_or_b32 s14, s14, s15
	v_or_b32_e32 v4, s14, v68
	v_add_u32_e32 v4, s34, v4
	v_mov_b32_e32 v5, v1
	v_lshlrev_b64 v[4:5], 8, v[4:5]
	v_lshl_add_u64 v[4:5], s[0:1], 0, v[4:5]
	v_lshlrev_b32_e32 v38, 1, v3
	v_mov_b32_e32 v39, v1
	v_lshl_add_u64 v[4:5], v[4:5], 0, v[38:39]
	global_store_dwordx4 v[4:5], v[26:29], off
	global_store_dwordx4 v[4:5], v[30:33], off offset:256
